# v47 + P0 transposes of w_gate_up and w_in walk items in 2-D blocks (64 k-blocks x 32 n-blocks) so concurrent waves write whole destination rows
# baseline (speedup 1.0000x reference)
.LBB0_22:
	s_andn2_b64 vcc, exec, s[6:7]
	s_cbranch_vccnz .LBB0_26
	s_add_i32 s81, s80, 0x5780
	s_and_b32 s81, s81, 0xffff
	s_cmp_lt_u32 s81, 0xa800
	s_cbranch_scc0 .Lgu_tail
	s_lshr_b32 s16, s81, 11
	s_bfe_u32 s82, s81, 0x60005
	s_and_b32 s83, s81, 31
	s_lshl_b32 s16, s16, 5
	s_add_i32 s83, s83, s16
	s_mul_i32 s82, s82, 0x2b0
	s_add_i32 s81, s82, s83
	s_branch .Lgu_done
.Lgu_tail:
	s_sub_i32 s16, s81, 0xa800
	s_lshr_b32 s82, s16, 4
	s_and_b32 s83, s16, 15
	s_mul_i32 s82, s82, 0x2b0
	s_add_i32 s81, s82, s83
	s_add_i32 s81, s81, 0x2a0
.Lgu_done:
	s_and_b32 s16, s81, 0xffff
	s_mul_i32 s16, s16, 0xbe83
	s_lshr_b32 s16, s16, 25
	s_load_dwordx4 s[8:11], s[0:1], 0x78
	s_load_dwordx2 s[84:85], s[0:1], 0x88
	s_load_dwordx2 s[6:7], s[0:1], 0xc0
	s_mul_i32 s82, s16, 0x2b0
	s_sub_i32 s83, s81, s82
	s_lshl_b32 s81, s83, 5
	s_lshl_b32 s82, s16, 6
	s_and_b32 s81, s81, 0xffe0
	v_or_b32_e32 v71, s81, v65
	v_add_u32_e32 v2, s82, v74
	s_waitcnt lgkmcnt(0)
	v_mov_b64_e32 v[0:1], s[84:85]
	s_mov_b32 s84, 0x15800
	v_mad_i64_i32 v[0:1], s[84:85], v2, s84, v[0:1]
	v_lshlrev_b32_e32 v68, 2, v71
	v_lshl_add_u64 v[72:73], v[0:1], 0, v[68:69]
	s_mov_b32 s84, 0x2b000
	v_add_co_u32_e32 v0, vcc, s84, v72
	s_mov_b32 s84, 0x56000
	s_nop 0
	v_addc_co_u32_e32 v1, vcc, 0, v73, vcc
	v_add_co_u32_e32 v2, vcc, s84, v72
	s_mov_b32 s84, 0x81000
	s_nop 0
	v_addc_co_u32_e32 v3, vcc, 0, v73, vcc
	v_add_co_u32_e32 v4, vcc, s84, v72
	s_mov_b32 s84, 0xac000
	s_nop 0
	v_addc_co_u32_e32 v5, vcc, 0, v73, vcc
	v_add_co_u32_e32 v6, vcc, s84, v72
	s_mov_b32 s84, 0xd7000
	s_nop 0
	v_addc_co_u32_e32 v7, vcc, 0, v73, vcc
	v_add_co_u32_e32 v8, vcc, s84, v72
	s_mov_b32 s84, 0x102000
	s_nop 0
	v_addc_co_u32_e32 v9, vcc, 0, v73, vcc
	v_add_co_u32_e32 v10, vcc, s84, v72
	s_mov_b32 s84, 0x12d000
	s_nop 0
	v_addc_co_u32_e32 v11, vcc, 0, v73, vcc
	v_add_co_u32_e32 v12, vcc, s84, v72
	s_mov_b32 s84, 0x158000
	s_nop 0
	v_addc_co_u32_e32 v13, vcc, 0, v73, vcc
	global_load_dword v68, v[72:73], off
	global_load_dword v91, v[0:1], off
	global_load_dword v92, v[2:3], off
	global_load_dword v93, v[4:5], off
	global_load_dword v94, v[6:7], off
	global_load_dword v95, v[8:9], off
	global_load_dword v96, v[10:11], off
	global_load_dword v97, v[12:13], off
	v_add_co_u32_e32 v0, vcc, s84, v72
	s_mov_b32 s84, 0x183000
	s_nop 0
	v_addc_co_u32_e32 v1, vcc, 0, v73, vcc
	v_add_co_u32_e32 v2, vcc, s84, v72
	s_mov_b32 s84, 0x1ae000
	s_nop 0
	v_addc_co_u32_e32 v3, vcc, 0, v73, vcc
	v_add_co_u32_e32 v4, vcc, s84, v72
	s_mov_b32 s84, 0x1d9000
	s_nop 0
	v_addc_co_u32_e32 v5, vcc, 0, v73, vcc
	v_add_co_u32_e32 v6, vcc, s84, v72
	s_mov_b32 s84, 0x204000
	s_nop 0
	v_addc_co_u32_e32 v7, vcc, 0, v73, vcc
	v_add_co_u32_e32 v8, vcc, s84, v72
	s_mov_b32 s84, 0x22f000
	s_nop 0
	v_addc_co_u32_e32 v9, vcc, 0, v73, vcc
	v_add_co_u32_e32 v10, vcc, s84, v72
	s_mov_b32 s84, 0x25a000
	s_nop 0
	v_addc_co_u32_e32 v11, vcc, 0, v73, vcc
	v_add_co_u32_e32 v12, vcc, s84, v72
	s_mov_b32 s84, 0x285000
	s_nop 0
	v_addc_co_u32_e32 v13, vcc, 0, v73, vcc
	v_add_co_u32_e32 v14, vcc, s84, v72
	s_mov_b32 s84, 0x2b0000
	s_nop 0
	v_addc_co_u32_e32 v15, vcc, 0, v73, vcc
	global_load_dword v98, v[0:1], off
	global_load_dword v99, v[2:3], off
	global_load_dword v100, v[4:5], off
	global_load_dword v101, v[6:7], off
	global_load_dword v102, v[8:9], off
	global_load_dword v103, v[10:11], off
	global_load_dword v104, v[12:13], off
	global_load_dword v105, v[14:15], off
	v_add_co_u32_e32 v0, vcc, s84, v72
	s_mov_b32 s84, 0x2db000
	s_nop 0
	v_addc_co_u32_e32 v1, vcc, 0, v73, vcc
	v_add_co_u32_e32 v2, vcc, s84, v72
	s_mov_b32 s84, 0x306000
	s_nop 0
	v_addc_co_u32_e32 v3, vcc, 0, v73, vcc
	v_add_co_u32_e32 v4, vcc, s84, v72
	s_lshl_b32 s84, s16, 8
	v_mov_b32_e32 v120, s84
	global_load_dwordx4 v[40:43], v120, s[8:9]
	global_load_dwordx4 v[60:63], v120, s[10:11]
	v_addc_co_u32_e32 v5, vcc, 0, v73, vcc
	s_mov_b32 s84, 0x331000
	v_add_co_u32_e32 v6, vcc, s84, v72
	global_load_dwordx4 v[52:55], v120, s[8:9] offset:16
	global_load_dwordx4 v[56:59], v120, s[10:11] offset:16
	v_addc_co_u32_e32 v7, vcc, 0, v73, vcc
	s_mov_b32 s84, 0x35c000
	v_add_co_u32_e32 v8, vcc, s84, v72
	global_load_dwordx4 v[44:47], v120, s[8:9] offset:32
	global_load_dwordx4 v[48:51], v120, s[10:11] offset:32
	v_addc_co_u32_e32 v9, vcc, 0, v73, vcc
	s_mov_b32 s84, 0x387000
	v_add_co_u32_e32 v10, vcc, s84, v72
	s_mov_b32 s84, 0x3b2000
	s_nop 0
	v_addc_co_u32_e32 v11, vcc, 0, v73, vcc
	v_add_co_u32_e32 v12, vcc, s84, v72
	s_mov_b32 s84, 0x3dd000
	s_nop 0
	v_addc_co_u32_e32 v13, vcc, 0, v73, vcc
	v_add_co_u32_e32 v14, vcc, s84, v72
	s_mov_b32 s84, 0x408000
	s_nop 0
	v_addc_co_u32_e32 v15, vcc, 0, v73, vcc
	global_load_dword v106, v[0:1], off
	global_load_dword v107, v[2:3], off
	global_load_dword v108, v[4:5], off
	global_load_dword v109, v[6:7], off
	global_load_dword v110, v[8:9], off
	global_load_dword v111, v[10:11], off
	global_load_dword v112, v[12:13], off
	global_load_dword v113, v[14:15], off
	global_load_dwordx4 v[0:3], v120, s[8:9] offset:48
	global_load_dwordx4 v[4:7], v120, s[10:11] offset:48
	s_nop 0
	global_load_dwordx4 v[8:11], v120, s[8:9] offset:64
	global_load_dwordx4 v[36:39], v120, s[10:11] offset:64
	v_add_co_u32_e32 v114, vcc, s84, v72
	s_mov_b32 s84, 0x433000
	s_nop 0
	v_addc_co_u32_e32 v115, vcc, 0, v73, vcc
	v_add_co_u32_e32 v116, vcc, s84, v72
	s_mov_b32 s84, 0x45e000
	s_nop 0
	v_addc_co_u32_e32 v117, vcc, 0, v73, vcc
	v_add_co_u32_e32 v118, vcc, s84, v72
	s_mov_b32 s84, 0x489000
	s_nop 0
	v_addc_co_u32_e32 v119, vcc, 0, v73, vcc
	v_add_co_u32_e32 v122, vcc, s84, v72
	s_mov_b32 s84, 0x4b4000
	s_nop 0
	v_addc_co_u32_e32 v123, vcc, 0, v73, vcc
	v_add_co_u32_e32 v124, vcc, s84, v72
	global_load_dwordx4 v[24:27], v120, s[8:9] offset:80
	global_load_dwordx4 v[32:35], v120, s[10:11] offset:80
	v_addc_co_u32_e32 v125, vcc, 0, v73, vcc
	s_mov_b32 s84, 0x4df000
	v_add_co_u32_e32 v126, vcc, s84, v72
	global_load_dwordx4 v[12:15], v120, s[8:9] offset:96
	global_load_dwordx4 v[16:19], v120, s[10:11] offset:96
	v_addc_co_u32_e32 v127, vcc, 0, v73, vcc
	s_mov_b32 s84, 0x50a000
	v_add_co_u32_e32 v128, vcc, s84, v72
	global_load_dwordx4 v[20:23], v120, s[8:9] offset:112
	global_load_dwordx4 v[28:31], v120, s[10:11] offset:112
	v_addc_co_u32_e32 v129, vcc, 0, v73, vcc
	s_mov_b32 s84, 0x535000
	v_add_co_u32_e32 v130, vcc, s84, v72
	s_waitcnt vmcnt(23)
	v_cndmask_b32_e64 v40, v41, v40, s[4:5]
	v_addc_co_u32_e32 v131, vcc, 0, v73, vcc
	global_load_dword v72, v[114:115], off
	global_load_dword v73, v[116:117], off
	s_nop 0
	global_load_dword v114, v[118:119], off
	global_load_dword v115, v[122:123], off
	global_load_dword v116, v[124:125], off
	global_load_dword v117, v[126:127], off
	s_nop 0
	global_load_dword v118, v[128:129], off
	global_load_dword v119, v[130:131], off
	global_load_dwordx4 v[122:125], v120, s[8:9] offset:128
	s_nop 0
	global_load_dwordx4 v[126:129], v120, s[10:11] offset:128
	s_waitcnt vmcnt(32)
	v_cndmask_b32_e64 v41, v61, v60, s[4:5]
	global_load_dwordx4 v[130:133], v120, s[8:9] offset:144
	global_load_dwordx4 v[134:137], v120, s[10:11] offset:144
	v_fma_f32 v60, v68, v41, 0
	v_cndmask_b32_e64 v41, v43, v42, s[4:5]
	v_cndmask_b32_e64 v42, v63, v62, s[4:5]
	v_fmac_f32_e32 v60, v91, v42
	s_waitcnt vmcnt(32)
	v_cndmask_b32_e64 v43, v57, v56, s[4:5]
	global_load_dwordx4 v[138:141], v120, s[8:9] offset:160
	global_load_dwordx4 v[142:145], v120, s[10:11] offset:160
	v_cndmask_b32_e64 v42, v53, v52, s[4:5]
	v_fmac_f32_e32 v60, v92, v43
	v_cndmask_b32_e64 v52, v59, v58, s[4:5]
	v_cndmask_b32_e64 v43, v55, v54, s[4:5]
	v_fmac_f32_e32 v60, v93, v52
	s_waitcnt vmcnt(33)
	v_cndmask_b32_e64 v44, v45, v44, s[4:5]
	s_waitcnt vmcnt(32)
	v_cndmask_b32_e64 v45, v49, v48, s[4:5]
	global_load_dwordx4 v[52:55], v120, s[8:9] offset:176
	global_load_dwordx4 v[56:59], v120, s[10:11] offset:176
	v_fmac_f32_e32 v60, v94, v45
	v_cndmask_b32_e64 v45, v47, v46, s[4:5]
	v_cndmask_b32_e64 v46, v51, v50, s[4:5]
	v_fmac_f32_e32 v60, v95, v46
	global_load_dwordx4 v[46:49], v120, s[8:9] offset:192
	global_load_dwordx4 v[146:149], v120, s[10:11] offset:192
	global_load_dwordx4 v[150:153], v120, s[8:9] offset:208
	global_load_dwordx4 v[154:157], v120, s[10:11] offset:208
	global_load_dwordx4 v[158:161], v120, s[8:9] offset:224
	global_load_dwordx4 v[162:165], v120, s[10:11] offset:224
	v_fma_f32 v61, v68, v40, 0
	v_fmac_f32_e32 v61, v91, v41
	v_fmac_f32_e32 v61, v92, v42
	v_fmac_f32_e32 v61, v93, v43
	v_fmac_f32_e32 v61, v94, v44
	s_waitcnt vmcnt(31)
	v_cndmask_b32_e64 v0, v1, v0, s[4:5]
	s_waitcnt vmcnt(30)
	v_cndmask_b32_e64 v1, v5, v4, s[4:5]
	v_fmac_f32_e32 v60, v96, v1
	v_cndmask_b32_e64 v1, v3, v2, s[4:5]
	s_waitcnt vmcnt(28)
	v_cndmask_b32_e64 v3, v37, v36, s[4:5]
	v_cndmask_b32_e64 v4, v39, v38, s[4:5]
	global_load_dwordx4 v[36:39], v120, s[8:9] offset:240
	global_load_dwordx4 v[166:169], v120, s[10:11] offset:240
	v_fmac_f32_e32 v61, v95, v45
	v_fmac_f32_e32 v61, v96, v0
	v_cndmask_b32_e64 v2, v7, v6, s[4:5]
	v_fmac_f32_e32 v60, v97, v2
	v_fmac_f32_e32 v61, v97, v1
	v_cndmask_b32_e64 v2, v9, v8, s[4:5]
	v_fmac_f32_e32 v60, v98, v3
	v_fmac_f32_e32 v61, v98, v2
	v_cndmask_b32_e64 v3, v11, v10, s[4:5]
	v_fmac_f32_e32 v60, v99, v4
	v_fmac_f32_e32 v61, v99, v3
	s_waitcnt vmcnt(29)
	v_cndmask_b32_e64 v4, v25, v24, s[4:5]
	s_waitcnt vmcnt(28)
	v_cndmask_b32_e64 v5, v33, v32, s[4:5]
	v_fmac_f32_e32 v60, v100, v5
	v_fmac_f32_e32 v61, v100, v4
	v_cndmask_b32_e64 v5, v27, v26, s[4:5]
	v_cndmask_b32_e64 v6, v35, v34, s[4:5]
	v_fmac_f32_e32 v60, v101, v6
	v_fmac_f32_e32 v61, v101, v5
	s_waitcnt vmcnt(27)
	v_cndmask_b32_e64 v6, v13, v12, s[4:5]
	s_waitcnt vmcnt(26)
	v_cndmask_b32_e64 v7, v17, v16, s[4:5]
	v_fmac_f32_e32 v60, v102, v7
	v_fmac_f32_e32 v61, v102, v6
	v_cndmask_b32_e64 v7, v15, v14, s[4:5]
	v_cndmask_b32_e64 v8, v19, v18, s[4:5]
	v_fmac_f32_e32 v60, v103, v8
	v_fmac_f32_e32 v61, v103, v7
	s_waitcnt vmcnt(25)
	v_cndmask_b32_e64 v8, v21, v20, s[4:5]
	s_waitcnt vmcnt(24)
	v_cndmask_b32_e64 v9, v29, v28, s[4:5]
	v_fmac_f32_e32 v60, v104, v9
	v_fmac_f32_e32 v61, v104, v8
	v_cndmask_b32_e64 v9, v23, v22, s[4:5]
	v_cndmask_b32_e64 v10, v31, v30, s[4:5]
	v_fmac_f32_e32 v60, v105, v10
	v_fmac_f32_e32 v61, v105, v9
	s_waitcnt vmcnt(15)
	v_cndmask_b32_e64 v10, v123, v122, s[4:5]
	s_waitcnt vmcnt(14)
	v_cndmask_b32_e64 v11, v127, v126, s[4:5]
	v_fmac_f32_e32 v60, v106, v11
	v_fmac_f32_e32 v61, v106, v10
	v_cndmask_b32_e64 v11, v125, v124, s[4:5]
	v_cndmask_b32_e64 v12, v129, v128, s[4:5]
	v_fmac_f32_e32 v60, v107, v12
	v_fmac_f32_e32 v61, v107, v11
	s_waitcnt vmcnt(13)
	v_cndmask_b32_e64 v12, v131, v130, s[4:5]
	s_waitcnt vmcnt(12)
	v_cndmask_b32_e64 v13, v135, v134, s[4:5]
	v_fmac_f32_e32 v60, v108, v13
	v_fmac_f32_e32 v61, v108, v12
	v_cndmask_b32_e64 v13, v133, v132, s[4:5]
	v_cndmask_b32_e64 v14, v137, v136, s[4:5]
	v_fmac_f32_e32 v60, v109, v14
	v_fmac_f32_e32 v61, v109, v13
	s_waitcnt vmcnt(11)
	v_cndmask_b32_e64 v14, v139, v138, s[4:5]
	s_waitcnt vmcnt(10)
	v_cndmask_b32_e64 v15, v143, v142, s[4:5]
	v_fmac_f32_e32 v60, v110, v15
	v_fmac_f32_e32 v61, v110, v14
	v_cndmask_b32_e64 v15, v141, v140, s[4:5]
	v_cndmask_b32_e64 v16, v145, v144, s[4:5]
	v_fmac_f32_e32 v60, v111, v16
	v_fmac_f32_e32 v61, v111, v15
	s_waitcnt vmcnt(9)
	v_cndmask_b32_e64 v16, v53, v52, s[4:5]
	s_waitcnt vmcnt(8)
	v_cndmask_b32_e64 v17, v57, v56, s[4:5]
	v_fmac_f32_e32 v60, v112, v17
	v_fmac_f32_e32 v61, v112, v16
	v_cndmask_b32_e64 v17, v55, v54, s[4:5]
	v_cndmask_b32_e64 v18, v59, v58, s[4:5]
	v_fmac_f32_e32 v60, v113, v18
	v_fmac_f32_e32 v61, v113, v17
	s_waitcnt vmcnt(7)
	v_cndmask_b32_e64 v18, v47, v46, s[4:5]
	s_waitcnt vmcnt(6)
	v_cndmask_b32_e64 v19, v147, v146, s[4:5]
	v_fmac_f32_e32 v60, v72, v19
	v_fmac_f32_e32 v61, v72, v18
	v_cndmask_b32_e64 v19, v49, v48, s[4:5]
	v_cndmask_b32_e64 v20, v149, v148, s[4:5]
	v_fmac_f32_e32 v60, v73, v20
	v_fmac_f32_e32 v61, v73, v19
	s_waitcnt vmcnt(5)
	v_cndmask_b32_e64 v20, v151, v150, s[4:5]
	s_waitcnt vmcnt(4)
	v_cndmask_b32_e64 v21, v155, v154, s[4:5]
	v_fmac_f32_e32 v60, v114, v21
	v_fmac_f32_e32 v61, v114, v20
	v_cndmask_b32_e64 v21, v153, v152, s[4:5]
	v_cndmask_b32_e64 v22, v157, v156, s[4:5]
	v_fmac_f32_e32 v60, v115, v22
	v_fmac_f32_e32 v61, v115, v21
	s_waitcnt vmcnt(3)
	v_cndmask_b32_e64 v22, v159, v158, s[4:5]
	s_waitcnt vmcnt(2)
	v_cndmask_b32_e64 v23, v163, v162, s[4:5]
	v_fmac_f32_e32 v60, v116, v23
	v_fmac_f32_e32 v61, v116, v22
	v_cndmask_b32_e64 v23, v161, v160, s[4:5]
	v_cndmask_b32_e64 v24, v165, v164, s[4:5]
	v_fmac_f32_e32 v60, v117, v24
	v_fmac_f32_e32 v61, v117, v23
	s_waitcnt vmcnt(1)
	v_cndmask_b32_e64 v24, v37, v36, s[4:5]
	s_waitcnt vmcnt(0)
	v_cndmask_b32_e64 v25, v167, v166, s[4:5]
	v_fmac_f32_e32 v60, v118, v25
	v_fmac_f32_e32 v61, v118, v24
	v_cndmask_b32_e64 v25, v39, v38, s[4:5]
	v_cndmask_b32_e64 v26, v169, v168, s[4:5]
	v_fmac_f32_e32 v60, v119, v26
	v_fmac_f32_e32 v61, v119, v25
	ds_bpermute_b32 v26, v81, v61
	ds_bpermute_b32 v27, v81, v60
	s_and_saveexec_b64 s[8:9], s[4:5]
	s_cbranch_execz .LBB0_25
	s_and_b32 s10, 0xffff, s83
	s_cmpk_gt_u32 s10, 0x157
	s_waitcnt lgkmcnt(1)
	v_add_f32_e32 v31, v61, v26
	v_add_u32_e32 v26, 0xffffd500, v71
	s_cselect_b64 vcc, -1, 0
	v_cndmask_b32_e32 v26, v71, v26, vcc
	s_waitcnt lgkmcnt(0)
	v_add_f32_e32 v30, v60, v27
	v_lshlrev_b32_e32 v27, 1, v26
	s_and_b64 s[10:11], vcc, exec
	v_and_b32_e32 v27, 0xffffff00, v27
	v_and_b32_e32 v26, 0x7f, v26
	s_cselect_b32 s10, 0x80, 0
	v_or3_b32 v26, v26, s10, v27
	s_mulk_i32 s16, 0x6600
	v_ashrrev_i32_e32 v27, 31, v26
	v_lshl_add_u64 v[26:27], v[26:27], 0, s[16:17]
	v_lshl_add_u64 v[26:27], v[26:27], 2, s[6:7]
	v_add_co_u32_e32 v28, vcc, 0x4bc00000, v26
	s_nop 1
	v_addc_co_u32_e32 v29, vcc, 0, v27, vcc
	v_add_co_u32_e32 v26, vcc, 0x4c260000, v26
	global_store_dword v[28:29], v31, off
	s_nop 0
	v_addc_co_u32_e32 v27, vcc, 0, v27, vcc
	global_store_dword v[26:27], v30, off

.LBB0_35:
	s_andn2_b64 vcc, exec, s[6:7]
	s_cbranch_vccnz .LBB0_8
	s_load_dwordx2 s[6:7], s[0:1], 0x38
	s_cmpk_lt_u32 s80, 0x6800
	s_cbranch_scc0 .Lwin_tail
	s_lshr_b32 s10, s80, 11
	s_bfe_u32 s9, s80, 0x60005
	s_and_b32 s8, s80, 31
	s_lshl_b32 s10, s10, 5
	s_add_i32 s10, s10, s8
	s_branch .Lwin_done
.Lwin_tail:
	s_sub_i32 s10, s80, 0x6800
	s_lshr_b32 s9, s10, 1
	s_and_b32 s10, s10, 1
	s_add_i32 s10, s10, 0x1a0
.Lwin_done:
	s_lshl_b32 s8, s9, 6
	s_lshl_b32 s10, s10, 5
	v_add_u32_e32 v3, s8, v74
	s_waitcnt lgkmcnt(0)
	v_mov_b64_e32 v[0:1], s[6:7]
	s_mov_b32 s6, 0xd0c0
	v_mad_i64_i32 v[0:1], s[6:7], v3, s6, v[0:1]
	v_add_u32_e32 v2, s10, v65
	s_movk_i32 s6, 0x3430
	v_cmp_gt_i32_e32 vcc, s6, v2
	s_mov_b32 s6, 0x1a000
	s_ashr_i32 s9, s8, 31
	v_cndmask_b32_e32 v2, 0, v2, vcc
	v_ashrrev_i32_e32 v3, 31, v2
	v_lshl_add_u64 v[30:31], v[2:3], 2, v[0:1]
	v_add_co_u32_e64 v0, s[6:7], s6, v30
	s_lshl_b64 s[8:9], s[8:9], 1
	s_nop 0
	v_addc_co_u32_e64 v1, s[6:7], 0, v31, s[6:7]
	s_mov_b32 s6, 0x34000
	s_nop 0
	v_add_co_u32_e64 v2, s[6:7], s6, v30
	v_mov_b32_e32 v71, v69
	s_nop 0
	v_addc_co_u32_e64 v3, s[6:7], 0, v31, s[6:7]
	s_mov_b32 s6, 0x4e000
	s_nop 0
	v_add_co_u32_e64 v8, s[6:7], s6, v30
	s_nop 1
	v_addc_co_u32_e64 v9, s[6:7], 0, v31, s[6:7]
	v_add_co_u32_e64 v10, s[6:7], s48, v30
	s_nop 1
	v_addc_co_u32_e64 v11, s[6:7], 0, v31, s[6:7]
	s_mov_b32 s6, 0x82000
	s_nop 0
	v_add_co_u32_e64 v12, s[6:7], s6, v30
	s_nop 1
	v_addc_co_u32_e64 v13, s[6:7], 0, v31, s[6:7]
	s_mov_b32 s6, 0x9c000
	s_nop 0
	v_add_co_u32_e64 v14, s[6:7], s6, v30
	s_nop 1
	v_addc_co_u32_e64 v15, s[6:7], 0, v31, s[6:7]
	s_mov_b32 s6, 0xb6000
	s_nop 0
	v_add_co_u32_e64 v16, s[6:7], s6, v30
	s_nop 1
	v_addc_co_u32_e64 v17, s[6:7], 0, v31, s[6:7]
	global_load_dword v6, v[30:31], off
	global_load_dword v7, v[0:1], off offset:384
	global_load_dword v4, v[2:3], off offset:768
	global_load_dword v5, v[8:9], off offset:1152
	s_nop 0
	global_load_dword v2, v[10:11], off offset:1536
	global_load_dword v3, v[12:13], off offset:1920
	global_load_dword v0, v[14:15], off offset:2304
	global_load_dword v1, v[16:17], off offset:2688
	v_add_co_u32_e64 v8, s[6:7], s61, v30
	s_waitcnt vmcnt(7)
	v_cndmask_b32_e32 v6, 0, v6, vcc
	v_addc_co_u32_e64 v9, s[6:7], 0, v31, s[6:7]
	s_mov_b32 s6, 0xea000
	s_nop 0
	v_add_co_u32_e64 v10, s[6:7], s6, v30
	s_waitcnt vmcnt(1)
	v_cndmask_b32_e32 v0, 0, v0, vcc
	v_addc_co_u32_e64 v11, s[6:7], 0, v31, s[6:7]
	s_mov_b32 s6, 0x104000
	s_nop 0
	v_add_co_u32_e64 v12, s[6:7], s6, v30
	s_waitcnt vmcnt(0)
	v_cndmask_b32_e32 v1, 0, v1, vcc
	v_addc_co_u32_e64 v13, s[6:7], 0, v31, s[6:7]
	s_mov_b32 s6, 0x11f000
	s_nop 0
	v_add_co_u32_e64 v16, s[6:7], s6, v30
	v_cndmask_b32_e32 v7, 0, v7, vcc
	s_nop 0
	v_addc_co_u32_e64 v17, s[6:7], 0, v31, s[6:7]
	s_mov_b32 s6, 0x139000
	s_nop 0
	v_add_co_u32_e64 v18, s[6:7], s6, v30
	v_cndmask_b32_e32 v4, 0, v4, vcc
	s_nop 0
	v_addc_co_u32_e64 v19, s[6:7], 0, v31, s[6:7]
	s_mov_b32 s6, 0x153000
	s_nop 0
	v_add_co_u32_e64 v20, s[6:7], s6, v30
	v_cndmask_b32_e32 v5, 0, v5, vcc
	s_nop 0
	v_addc_co_u32_e64 v21, s[6:7], 0, v31, s[6:7]
	s_mov_b32 s6, 0x16d000
	s_nop 0
	v_add_co_u32_e64 v22, s[6:7], s6, v30
	v_cndmask_b32_e32 v2, 0, v2, vcc
	s_nop 0
	v_addc_co_u32_e64 v23, s[6:7], 0, v31, s[6:7]
	s_mov_b32 s6, 0x187000
	s_nop 0
	v_add_co_u32_e64 v24, s[6:7], s6, v30
	v_cndmask_b32_e32 v3, 0, v3, vcc
	s_nop 0
	v_addc_co_u32_e64 v25, s[6:7], 0, v31, s[6:7]
	s_mov_b32 s6, 0x1a1000
	global_load_dword v14, v[8:9], off offset:3072
	global_load_dword v15, v[10:11], off offset:3456
	s_nop 0
	global_load_dword v12, v[12:13], off offset:3840
	s_nop 0
	global_load_dword v13, v[16:17], off offset:128
	global_load_dword v10, v[18:19], off offset:512
	global_load_dword v11, v[20:21], off offset:896
	global_load_dword v8, v[22:23], off offset:1280
	global_load_dword v9, v[24:25], off offset:1664
	v_add_co_u32_e64 v16, s[6:7], s6, v30
	s_nop 1
	v_addc_co_u32_e64 v17, s[6:7], 0, v31, s[6:7]
	s_mov_b32 s6, 0x1bb000
	s_nop 0
	v_add_co_u32_e64 v18, s[6:7], s6, v30
	s_nop 1
	v_addc_co_u32_e64 v19, s[6:7], 0, v31, s[6:7]
	s_mov_b32 s6, 0x1d5000
	s_nop 0
	v_add_co_u32_e64 v20, s[6:7], s6, v30
	s_nop 1
	v_addc_co_u32_e64 v21, s[6:7], 0, v31, s[6:7]
	s_mov_b32 s6, 0x1ef000
	s_nop 0
	v_add_co_u32_e64 v24, s[6:7], s6, v30
	s_nop 1
	v_addc_co_u32_e64 v25, s[6:7], 0, v31, s[6:7]
	s_mov_b32 s6, 0x209000
	s_nop 0
	v_add_co_u32_e64 v26, s[6:7], s6, v30
	s_nop 1
	v_addc_co_u32_e64 v27, s[6:7], 0, v31, s[6:7]
	s_mov_b32 s6, 0x223000
	s_nop 0
	v_add_co_u32_e64 v28, s[6:7], s6, v30
	s_nop 1
	v_addc_co_u32_e64 v29, s[6:7], 0, v31, s[6:7]
	s_mov_b32 s6, 0x23e000
	s_nop 0
	v_add_co_u32_e64 v32, s[6:7], s6, v30
	s_nop 1
	v_addc_co_u32_e64 v33, s[6:7], 0, v31, s[6:7]
	v_add_co_u32_e64 v34, s[6:7], s71, v30
	s_nop 1
	v_addc_co_u32_e64 v35, s[6:7], 0, v31, s[6:7]
	global_load_dword v22, v[16:17], off offset:2048
	global_load_dword v23, v[18:19], off offset:2432
	s_nop 0
	global_load_dword v20, v[20:21], off offset:2816
	s_nop 0
	global_load_dword v21, v[24:25], off offset:3200
	global_load_dword v18, v[26:27], off offset:3584
	global_load_dword v19, v[28:29], off offset:3968
	global_load_dword v16, v[32:33], off offset:256
	global_load_dword v17, v[34:35], off offset:640
	v_add_co_u32_e64 v24, s[6:7], s72, v30
	s_nop 1
	v_addc_co_u32_e64 v25, s[6:7], 0, v31, s[6:7]
	v_add_co_u32_e64 v26, s[6:7], s73, v30
	s_nop 1
	v_addc_co_u32_e64 v27, s[6:7], 0, v31, s[6:7]
	v_add_co_u32_e64 v32, s[6:7], s74, v30
	s_nop 1
	v_addc_co_u32_e64 v33, s[6:7], 0, v31, s[6:7]
	v_add_co_u32_e64 v34, s[6:7], s75, v30
	s_nop 1
	v_addc_co_u32_e64 v35, s[6:7], 0, v31, s[6:7]
	v_add_co_u32_e64 v36, s[6:7], s76, v30
	s_nop 1
	v_addc_co_u32_e64 v37, s[6:7], 0, v31, s[6:7]
	v_add_co_u32_e64 v38, s[6:7], s77, v30
	s_nop 1
	v_addc_co_u32_e64 v39, s[6:7], 0, v31, s[6:7]
	global_load_dword v28, v[24:25], off offset:1024
	global_load_dword v29, v[26:27], off offset:1408
	s_nop 0
	global_load_dword v26, v[32:33], off offset:1792
	global_load_dword v27, v[34:35], off offset:2176
	global_load_dword v24, v[36:37], off offset:2560
	global_load_dword v25, v[38:39], off offset:2944
	v_add_co_u32_e64 v32, s[6:7], s78, v30
	s_nop 1
	v_addc_co_u32_e64 v33, s[6:7], 0, v31, s[6:7]
	v_add_co_u32_e64 v34, s[6:7], s79, v30
	s_nop 1
	v_addc_co_u32_e64 v35, s[6:7], 0, v31, s[6:7]
	global_load_dword v30, v[32:33], off offset:3328
	global_load_dword v31, v[34:35], off offset:3712
	ds_write2_b32 v82, v0, v1 offset0:140 offset1:206
	s_waitcnt vmcnt(23)
	v_cndmask_b32_e32 v0, 0, v14, vcc
	s_waitcnt vmcnt(22)
	v_cndmask_b32_e32 v1, 0, v15, vcc
	ds_write2_b32 v83, v0, v1 offset0:16 offset1:82
	s_waitcnt vmcnt(21)
	v_cndmask_b32_e32 v0, 0, v12, vcc
	s_waitcnt vmcnt(20)
	v_cndmask_b32_e32 v1, 0, v13, vcc
	ds_write2_b32 v83, v0, v1 offset0:148 offset1:214
	s_waitcnt vmcnt(19)
	v_cndmask_b32_e32 v0, 0, v10, vcc
	s_waitcnt vmcnt(18)
	v_cndmask_b32_e32 v1, 0, v11, vcc
	ds_write2_b32 v84, v0, v1 offset0:24 offset1:90
	s_waitcnt vmcnt(17)
	v_cndmask_b32_e32 v0, 0, v8, vcc
	s_waitcnt vmcnt(16)
	v_cndmask_b32_e32 v1, 0, v9, vcc
	ds_write2_b32 v84, v0, v1 offset0:156 offset1:222
	s_load_dwordx2 s[6:7], s[0:1], 0xc0
	ds_write2_b32 v75, v6, v7 offset1:66
	ds_write2_b32 v75, v4, v5 offset0:132 offset1:198
	ds_write2_b32 v82, v2, v3 offset0:8 offset1:74
	s_waitcnt lgkmcnt(0)
	s_add_u32 s6, s6, s8
	s_addc_u32 s7, s7, s9
	s_waitcnt vmcnt(15)
	v_cndmask_b32_e32 v0, 0, v22, vcc
	s_waitcnt vmcnt(14)
	v_cndmask_b32_e32 v1, 0, v23, vcc
	ds_write2_b32 v85, v0, v1 offset0:32 offset1:98
	s_waitcnt vmcnt(13)
	v_cndmask_b32_e32 v0, 0, v20, vcc
	s_waitcnt vmcnt(12)
	v_cndmask_b32_e32 v1, 0, v21, vcc
	ds_write2_b32 v85, v0, v1 offset0:164 offset1:230
	s_waitcnt vmcnt(11)
	v_cndmask_b32_e32 v0, 0, v18, vcc
	s_waitcnt vmcnt(10)
	v_cndmask_b32_e32 v1, 0, v19, vcc
	ds_write2_b32 v86, v0, v1 offset0:40 offset1:106
	s_waitcnt vmcnt(9)
	v_cndmask_b32_e32 v0, 0, v16, vcc
	s_waitcnt vmcnt(8)
	v_cndmask_b32_e32 v1, 0, v17, vcc
	ds_write2_b32 v86, v0, v1 offset0:172 offset1:238
	v_add_u32_e32 v22, s10, v76
	v_ashrrev_i32_e32 v23, 31, v22
	s_waitcnt vmcnt(7)
	v_cndmask_b32_e32 v0, 0, v28, vcc
	s_waitcnt vmcnt(6)
	v_cndmask_b32_e32 v1, 0, v29, vcc
	ds_write2_b32 v87, v0, v1 offset0:48 offset1:114
	s_waitcnt vmcnt(5)
	v_cndmask_b32_e32 v0, 0, v26, vcc
	s_waitcnt vmcnt(4)
	v_cndmask_b32_e32 v1, 0, v27, vcc
	ds_write2_b32 v87, v0, v1 offset0:180 offset1:246
	s_waitcnt vmcnt(3)
	v_cndmask_b32_e32 v0, 0, v24, vcc
	s_waitcnt vmcnt(2)
	v_cndmask_b32_e32 v1, 0, v25, vcc
	ds_write2_b32 v88, v0, v1 offset0:56 offset1:122
	v_lshlrev_b64 v[24:25], 13, v[22:23]
	s_waitcnt vmcnt(1)
	v_cndmask_b32_e32 v0, 0, v30, vcc
	s_waitcnt vmcnt(0)
	v_cndmask_b32_e32 v1, 0, v31, vcc
	ds_write2_b32 v88, v0, v1 offset0:188 offset1:254
	s_waitcnt lgkmcnt(0)
	ds_read2_b32 v[4:5], v77 offset1:8
	ds_read2_b32 v[8:9], v77 offset0:33 offset1:41
	ds_read2_b32 v[10:11], v77 offset0:66 offset1:74
	v_lshl_add_u64 v[0:1], s[6:7], 0, v[70:71]
	ds_read2_b32 v[12:13], v77 offset0:99 offset1:107
	v_lshl_add_u64 v[6:7], v[0:1], 0, s[30:31]
	s_waitcnt lgkmcnt(3)
	v_bfe_u32 v0, v4, 16, 1
	v_add3_u32 v0, v4, v0, s35
	s_waitcnt lgkmcnt(2)
	v_bfe_u32 v1, v8, 16, 1
	ds_read2_b32 v[14:15], v77 offset0:132 offset1:140
	v_lshrrev_b32_e32 v0, 16, v0
	v_add3_u32 v1, v8, v1, s35
	ds_read2_b32 v[16:17], v77 offset0:165 offset1:173
	v_and_or_b32 v0, v1, s36, v0
	s_waitcnt lgkmcnt(3)
	v_bfe_u32 v1, v10, 16, 1
	v_add3_u32 v1, v10, v1, s35
	s_waitcnt lgkmcnt(2)
	v_bfe_u32 v2, v12, 16, 1
	ds_read2_b32 v[18:19], v77 offset0:198 offset1:206
	v_lshrrev_b32_e32 v1, 16, v1
	v_add3_u32 v2, v12, v2, s35
	ds_read2_b32 v[20:21], v77 offset0:231 offset1:239
	v_and_or_b32 v1, v2, s36, v1
	s_waitcnt lgkmcnt(3)
	v_bfe_u32 v2, v14, 16, 1
	v_add3_u32 v2, v14, v2, s35
	s_waitcnt lgkmcnt(2)
	v_bfe_u32 v3, v16, 16, 1
	v_lshrrev_b32_e32 v2, 16, v2
	v_add3_u32 v3, v16, v3, s35
	v_and_or_b32 v2, v3, s36, v2
	s_waitcnt lgkmcnt(1)
	v_bfe_u32 v3, v18, 16, 1
	v_add3_u32 v3, v18, v3, s35
	s_waitcnt lgkmcnt(0)
	v_bfe_u32 v4, v20, 16, 1
	v_lshrrev_b32_e32 v3, 16, v3
	v_add3_u32 v4, v20, v4, s35
	v_and_or_b32 v3, v4, s36, v3
	v_lshl_add_u64 v[24:25], v[6:7], 0, v[24:25]
	global_store_dwordx4 v[24:25], v[0:3], off
	v_bfe_u32 v4, v21, 16, 1
	v_add3_u32 v4, v21, v4, s35
	v_bfe_u32 v0, v5, 16, 1
	v_add3_u32 v0, v5, v0, s35
	v_bfe_u32 v1, v9, 16, 1
	v_lshrrev_b32_e32 v0, 16, v0
	v_add3_u32 v1, v9, v1, s35
	v_and_or_b32 v0, v1, s36, v0
	v_bfe_u32 v1, v11, 16, 1
	v_add3_u32 v1, v11, v1, s35
	v_bfe_u32 v2, v13, 16, 1
	v_lshrrev_b32_e32 v1, 16, v1
	v_add3_u32 v2, v13, v2, s35
	v_and_or_b32 v1, v2, s36, v1
	v_bfe_u32 v2, v15, 16, 1
	v_add3_u32 v2, v15, v2, s35
	v_bfe_u32 v3, v17, 16, 1
	v_lshrrev_b32_e32 v2, 16, v2
	v_add3_u32 v3, v17, v3, s35
	v_and_or_b32 v2, v3, s36, v2
	v_bfe_u32 v3, v19, 16, 1
	v_add3_u32 v3, v19, v3, s35
	v_lshrrev_b32_e32 v3, 16, v3
	v_and_or_b32 v3, v4, s36, v3
	v_add_u32_e32 v4, 8, v22
	v_ashrrev_i32_e32 v5, 31, v4
	v_lshlrev_b64 v[4:5], 13, v[4:5]
	ds_read2_b32 v[8:9], v77 offset0:16 offset1:24
	v_lshl_add_u64 v[4:5], v[6:7], 0, v[4:5]
	global_store_dwordx4 v[4:5], v[0:3], off
	ds_read2_b32 v[4:5], v77 offset0:49 offset1:57
	ds_read2_b32 v[10:11], v77 offset0:82 offset1:90
	ds_read2_b32 v[12:13], v77 offset0:115 offset1:123
	s_waitcnt lgkmcnt(3)
	v_bfe_u32 v0, v8, 16, 1
	v_add3_u32 v0, v8, v0, s35
	s_waitcnt lgkmcnt(2)
	v_bfe_u32 v1, v4, 16, 1
	ds_read2_b32 v[14:15], v77 offset0:148 offset1:156
	v_lshrrev_b32_e32 v0, 16, v0
	v_add3_u32 v1, v4, v1, s35
	ds_read2_b32 v[16:17], v77 offset0:181 offset1:189
	v_and_or_b32 v0, v1, s36, v0
	s_waitcnt lgkmcnt(3)
	v_bfe_u32 v1, v10, 16, 1
	v_add3_u32 v1, v10, v1, s35
	s_waitcnt lgkmcnt(2)
	v_bfe_u32 v2, v12, 16, 1
	ds_read2_b32 v[18:19], v77 offset0:214 offset1:222
	v_lshrrev_b32_e32 v1, 16, v1
	v_add3_u32 v2, v12, v2, s35
	ds_read2_b32 v[20:21], v77 offset0:247 offset1:255
	v_and_or_b32 v1, v2, s36, v1
	s_waitcnt lgkmcnt(3)
	v_bfe_u32 v2, v14, 16, 1
	v_add3_u32 v2, v14, v2, s35
	s_waitcnt lgkmcnt(2)
	v_bfe_u32 v3, v16, 16, 1
	v_lshrrev_b32_e32 v2, 16, v2
	v_add3_u32 v3, v16, v3, s35
	v_and_or_b32 v2, v3, s36, v2
	s_waitcnt lgkmcnt(1)
	v_bfe_u32 v3, v18, 16, 1
	v_add_u32_e32 v24, 16, v22
	v_add3_u32 v3, v18, v3, s35
	s_waitcnt lgkmcnt(0)
	v_bfe_u32 v4, v20, 16, 1
	v_ashrrev_i32_e32 v25, 31, v24
	v_lshrrev_b32_e32 v3, 16, v3
	v_add3_u32 v4, v20, v4, s35
	v_lshlrev_b64 v[24:25], 13, v[24:25]
	v_and_or_b32 v3, v4, s36, v3
	v_lshl_add_u64 v[24:25], v[6:7], 0, v[24:25]
	global_store_dwordx4 v[24:25], v[0:3], off
	v_bfe_u32 v4, v21, 16, 1
	v_add3_u32 v4, v21, v4, s35
	v_bfe_u32 v0, v9, 16, 1
	v_add3_u32 v0, v9, v0, s35
	v_bfe_u32 v1, v5, 16, 1
	v_lshrrev_b32_e32 v0, 16, v0
	v_add3_u32 v1, v5, v1, s35
	v_and_or_b32 v0, v1, s36, v0
	v_bfe_u32 v1, v11, 16, 1
	v_add3_u32 v1, v11, v1, s35
	v_bfe_u32 v2, v13, 16, 1
	v_lshrrev_b32_e32 v1, 16, v1
	v_add3_u32 v2, v13, v2, s35
	v_and_or_b32 v1, v2, s36, v1
	v_bfe_u32 v2, v15, 16, 1
	v_add3_u32 v2, v15, v2, s35
	v_bfe_u32 v3, v17, 16, 1
	v_lshrrev_b32_e32 v2, 16, v2
	v_add3_u32 v3, v17, v3, s35
	v_and_or_b32 v2, v3, s36, v2
	v_bfe_u32 v3, v19, 16, 1
	v_add3_u32 v3, v19, v3, s35
	v_lshrrev_b32_e32 v3, 16, v3
	v_and_or_b32 v3, v4, s36, v3
	v_add_u32_e32 v4, 24, v22
	v_ashrrev_i32_e32 v5, 31, v4
	v_lshlrev_b64 v[4:5], 13, v[4:5]
	v_lshl_add_u64 v[4:5], v[6:7], 0, v[4:5]
	global_store_dwordx4 v[4:5], v[0:3], off
	s_waitcnt lgkmcnt(0)
	s_branch .LBB0_8
